# E_UP/E_Q epilogues: row-scale loads hoisted, single wait, in-place pack and back-to-back stores
# speedup vs baseline: 1.0765x; 1.0044x over previous
.LBB0_894:
	s_add_i32 s6, s2, 2
	s_add_u32 s7, s64, s0
	s_addc_u32 s3, s65, s1
	s_add_u32 s8, s66, s0
	s_addc_u32 s9, s67, s1
	s_add_i32 s33, 0, 0x10000
	v_add_u32_e32 v160, s33, v165
	ds_read_b128 v[148:151], v160
	ds_read_b128 v[152:155], v160 offset:1024
	ds_read_b128 v[156:159], v160 offset:2048
	ds_read_b128 v[160:163], v160 offset:3072
	s_cmp_eq_u32 s92, s2
	s_cselect_b32 s2, s72, s7
	s_cselect_b32 s3, s73, s3
	s_cselect_b32 s9, s75, s9
	s_cselect_b32 s8, s74, s8
	v_lshl_add_u64 v[232:233], s[64:65], 0, v[132:133]
	s_add_i32 m0, s84, 0xc000
	ds_read_b128 v[196:199], v195
	ds_read_b128 v[200:203], v195 offset:1024
	ds_read_b128 v[204:207], v195 offset:2048
	ds_read_b128 v[208:211], v195 offset:3072
	ds_read_b128 v[212:215], v195 offset:4096
	ds_read_b128 v[216:219], v195 offset:5120
	ds_read_b128 v[220:223], v195 offset:6144
	ds_read_b128 v[224:227], v195 offset:7168
	global_load_lds_dwordx4 v[232:233], off
	v_lshl_add_u64 v[232:233], s[64:65], 0, v[134:135]
	s_add_i32 m0, s84, 0xe000
	s_nop 0
	global_load_lds_dwordx4 v[232:233], off
	s_waitcnt lgkmcnt(8)
	s_barrier
	s_waitcnt lgkmcnt(0)
	s_setprio 1
	s_waitcnt lgkmcnt(0)
	v_mfma_f32_16x16x32_bf16 v[128:131], v[148:151], v[196:199], v[128:131]
	v_mfma_f32_16x16x32_bf16 v[124:127], v[156:159], v[196:199], v[124:127]
	v_mfma_f32_16x16x32_bf16 v[108:111], v[148:151], v[204:207], v[108:111]
	v_mfma_f32_16x16x32_bf16 v[100:103], v[156:159], v[204:207], v[100:103]
	v_mfma_f32_16x16x32_bf16 v[88:91], v[148:151], v[212:215], v[88:91]
	v_mfma_f32_16x16x32_bf16 v[84:87], v[156:159], v[212:215], v[84:87]
	v_mfma_f32_16x16x32_bf16 v[56:59], v[148:151], v[220:223], v[56:59]
	v_mfma_f32_16x16x32_bf16 v[44:47], v[156:159], v[220:223], v[44:47]
	v_mfma_f32_16x16x32_bf16 v[128:131], v[152:155], v[200:203], v[128:131]
	v_mfma_f32_16x16x32_bf16 v[124:127], v[160:163], v[200:203], v[124:127]
	v_mfma_f32_16x16x32_bf16 v[108:111], v[152:155], v[208:211], v[108:111]
	v_mfma_f32_16x16x32_bf16 v[100:103], v[160:163], v[208:211], v[100:103]
	v_mfma_f32_16x16x32_bf16 v[88:91], v[152:155], v[216:219], v[88:91]
	v_mfma_f32_16x16x32_bf16 v[84:87], v[160:163], v[216:219], v[84:87]
	v_mfma_f32_16x16x32_bf16 v[56:59], v[152:155], v[224:227], v[56:59]
	v_mfma_f32_16x16x32_bf16 v[44:47], v[160:163], v[224:227], v[44:47]
	s_setprio 0
	s_barrier
	s_add_i32 s7, 0, 0x14000
	s_add_i32 s33, s33, s87
	v_lshl_add_u64 v[248:249], s[8:9], 0, v[138:139]
	s_add_u32 s8, s8, s34
	v_add_u32_e32 v244, s7, v165
	s_mov_b32 m0, s33
	s_addc_u32 s9, s9, s35
	ds_read_b128 v[232:235], v244
	ds_read_b128 v[236:239], v244 offset:1024
	ds_read_b128 v[240:243], v244 offset:2048
	ds_read_b128 v[244:247], v244 offset:3072
	global_load_lds_dwordx4 v[248:249], off
	v_lshl_add_u64 v[250:251], s[8:9], 0, v[138:139]
	s_add_i32 m0, s33, 0x2000
	s_nop 0
	global_load_lds_dwordx4 v[250:251], off
	s_barrier
	s_waitcnt lgkmcnt(0)
	s_setprio 1
	s_waitcnt lgkmcnt(0)
	v_mfma_f32_16x16x32_bf16 v[120:123], v[232:235], v[196:199], v[120:123]
	v_mfma_f32_16x16x32_bf16 v[116:119], v[240:243], v[196:199], v[116:119]
	v_mfma_f32_16x16x32_bf16 v[112:115], v[232:235], v[204:207], v[112:115]
	v_mfma_f32_16x16x32_bf16 v[104:107], v[240:243], v[204:207], v[104:107]
	v_mfma_f32_16x16x32_bf16 v[96:99], v[232:235], v[212:215], v[96:99]
	v_mfma_f32_16x16x32_bf16 v[92:95], v[240:243], v[212:215], v[92:95]
	v_mfma_f32_16x16x32_bf16 v[80:83], v[232:235], v[220:223], v[80:83]
	v_mfma_f32_16x16x32_bf16 v[76:79], v[240:243], v[220:223], v[76:79]
	v_mfma_f32_16x16x32_bf16 v[120:123], v[236:239], v[200:203], v[120:123]
	v_mfma_f32_16x16x32_bf16 v[116:119], v[244:247], v[200:203], v[116:119]
	v_mfma_f32_16x16x32_bf16 v[112:115], v[236:239], v[208:211], v[112:115]
	v_mfma_f32_16x16x32_bf16 v[104:107], v[244:247], v[208:211], v[104:107]
	v_mfma_f32_16x16x32_bf16 v[96:99], v[236:239], v[216:219], v[96:99]
	v_mfma_f32_16x16x32_bf16 v[92:95], v[244:247], v[216:219], v[92:95]
	v_mfma_f32_16x16x32_bf16 v[80:83], v[236:239], v[224:227], v[80:83]
	v_mfma_f32_16x16x32_bf16 v[76:79], v[244:247], v[224:227], v[76:79]
	s_setprio 0
	s_add_u32 s76, s2, s30
	s_mov_b32 m0, s84
	v_lshl_add_u64 v[250:251], s[2:3], 0, v[140:141]
	s_addc_u32 s77, s3, s31
	s_barrier
	ds_read_b128 v[196:199], v195 offset:16384
	ds_read_b128 v[200:203], v195 offset:17408
	ds_read_b128 v[204:207], v195 offset:18432
	ds_read_b128 v[208:211], v195 offset:19456
	ds_read_b128 v[212:215], v195 offset:20480
	ds_read_b128 v[216:219], v195 offset:21504
	ds_read_b128 v[220:223], v195 offset:22528
	ds_read_b128 v[224:227], v195 offset:23552
	global_load_lds_dwordx4 v[250:251], off
	v_lshl_add_u64 v[252:253], s[76:77], 0, v[140:141]
	s_mov_b32 m0, s93
	s_nop 0
	global_load_lds_dwordx4 v[252:253], off
	s_barrier
	s_waitcnt lgkmcnt(0)
	s_setprio 1
	s_waitcnt lgkmcnt(0)
	v_mfma_f32_16x16x32_bf16 v[64:67], v[148:151], v[196:199], v[64:67]
	v_mfma_f32_16x16x32_bf16 v[60:63], v[156:159], v[196:199], v[60:63]
	v_mfma_f32_16x16x32_bf16 v[40:43], v[148:151], v[204:207], v[40:43]
	v_mfma_f32_16x16x32_bf16 v[36:39], v[156:159], v[204:207], v[36:39]
	v_mfma_f32_16x16x32_bf16 v[22:25], v[148:151], v[212:215], v[22:25]
	v_mfma_f32_16x16x32_bf16 v[18:21], v[156:159], v[212:215], v[18:21]
	v_mfma_f32_16x16x32_bf16 v[6:9], v[148:151], v[220:223], v[6:9]
	v_mfma_f32_16x16x32_bf16 v[2:5], v[156:159], v[220:223], v[2:5]
	v_mfma_f32_16x16x32_bf16 v[64:67], v[152:155], v[200:203], v[64:67]
	v_mfma_f32_16x16x32_bf16 v[60:63], v[160:163], v[200:203], v[60:63]
	v_mfma_f32_16x16x32_bf16 v[40:43], v[152:155], v[208:211], v[40:43]
	v_mfma_f32_16x16x32_bf16 v[36:39], v[160:163], v[208:211], v[36:39]
	v_mfma_f32_16x16x32_bf16 v[22:25], v[152:155], v[216:219], v[22:25]
	v_mfma_f32_16x16x32_bf16 v[18:21], v[160:163], v[216:219], v[18:21]
	v_mfma_f32_16x16x32_bf16 v[6:9], v[152:155], v[224:227], v[6:9]
	v_mfma_f32_16x16x32_bf16 v[2:5], v[160:163], v[224:227], v[2:5]
	s_setprio 0
	s_barrier
	s_add_u32 s2, s8, s34
	s_addc_u32 s3, s9, s35
	s_add_i32 s7, s7, s87
	s_add_u32 s8, s2, s34
	v_lshl_add_u64 v[148:149], s[2:3], 0, v[138:139]
	s_mov_b32 m0, s7
	s_addc_u32 s9, s3, s35
	global_load_lds_dwordx4 v[148:149], off
	v_lshl_add_u64 v[252:253], s[8:9], 0, v[138:139]
	s_add_i32 m0, s7, 0x2000
	s_nop 0
	global_load_lds_dwordx4 v[252:253], off
	s_waitcnt vmcnt(6)
	s_barrier
	s_setprio 1
	v_mfma_f32_16x16x32_bf16 v[72:75], v[232:235], v[196:199], v[72:75]
	v_mfma_f32_16x16x32_bf16 v[68:71], v[240:243], v[196:199], v[68:71]
	v_mfma_f32_16x16x32_bf16 v[52:55], v[232:235], v[204:207], v[52:55]
	v_mfma_f32_16x16x32_bf16 v[48:51], v[240:243], v[204:207], v[48:51]
	v_mfma_f32_16x16x32_bf16 v[32:35], v[232:235], v[212:215], v[32:35]
	v_mfma_f32_16x16x32_bf16 v[28:31], v[240:243], v[212:215], v[28:31]
	v_mfma_f32_16x16x32_bf16 v[14:17], v[232:235], v[220:223], v[14:17]
	v_mfma_f32_16x16x32_bf16 v[10:13], v[240:243], v[220:223], v[10:13]
	v_mfma_f32_16x16x32_bf16 v[72:75], v[236:239], v[200:203], v[72:75]
	v_mfma_f32_16x16x32_bf16 v[68:71], v[244:247], v[200:203], v[68:71]
	v_mfma_f32_16x16x32_bf16 v[52:55], v[236:239], v[208:211], v[52:55]
	v_mfma_f32_16x16x32_bf16 v[48:51], v[244:247], v[208:211], v[48:51]
	v_mfma_f32_16x16x32_bf16 v[32:35], v[236:239], v[216:219], v[32:35]
	v_mfma_f32_16x16x32_bf16 v[28:31], v[244:247], v[216:219], v[28:31]
	v_mfma_f32_16x16x32_bf16 v[14:17], v[236:239], v[224:227], v[14:17]
	v_mfma_f32_16x16x32_bf16 v[10:13], v[244:247], v[224:227], v[10:13]
	s_setprio 0
	s_add_i32 s7, 0, 0x18000
	v_add_u32_e32 v160, s7, v165
	s_barrier
	ds_read_b128 v[148:151], v160
	ds_read_b128 v[152:155], v160 offset:1024
	ds_read_b128 v[156:159], v160 offset:2048
	ds_read_b128 v[160:163], v160 offset:3072
	s_add_u32 s8, s76, s30
	s_addc_u32 s9, s77, s31
	s_add_u32 s76, s8, s30
	s_mov_b32 m0, s28
	v_lshl_add_u64 v[232:233], s[8:9], 0, v[140:141]
	s_addc_u32 s77, s9, s31
	ds_read_b128 v[196:199], v195 offset:32768
	ds_read_b128 v[200:203], v195 offset:33792
	ds_read_b128 v[204:207], v195 offset:34816
	ds_read_b128 v[208:211], v195 offset:35840
	ds_read_b128 v[212:215], v195 offset:36864
	ds_read_b128 v[216:219], v195 offset:37888
	ds_read_b128 v[220:223], v195 offset:38912
	ds_read_b128 v[224:227], v195 offset:39936
	global_load_lds_dwordx4 v[232:233], off
	v_lshl_add_u64 v[232:233], s[76:77], 0, v[140:141]
	s_mov_b32 m0, s29
	s_nop 0
	global_load_lds_dwordx4 v[232:233], off
	s_waitcnt lgkmcnt(8)
	s_barrier
	s_waitcnt lgkmcnt(0)
	s_setprio 1
	s_waitcnt lgkmcnt(0)
	v_mfma_f32_16x16x32_bf16 v[128:131], v[148:151], v[196:199], v[128:131]
	v_mfma_f32_16x16x32_bf16 v[124:127], v[156:159], v[196:199], v[124:127]
	v_mfma_f32_16x16x32_bf16 v[108:111], v[148:151], v[204:207], v[108:111]
	v_mfma_f32_16x16x32_bf16 v[100:103], v[156:159], v[204:207], v[100:103]
	v_mfma_f32_16x16x32_bf16 v[88:91], v[148:151], v[212:215], v[88:91]
	v_mfma_f32_16x16x32_bf16 v[84:87], v[156:159], v[212:215], v[84:87]
	v_mfma_f32_16x16x32_bf16 v[56:59], v[148:151], v[220:223], v[56:59]
	v_mfma_f32_16x16x32_bf16 v[44:47], v[156:159], v[220:223], v[44:47]
	v_mfma_f32_16x16x32_bf16 v[128:131], v[152:155], v[200:203], v[128:131]
	v_mfma_f32_16x16x32_bf16 v[124:127], v[160:163], v[200:203], v[124:127]
	v_mfma_f32_16x16x32_bf16 v[108:111], v[152:155], v[208:211], v[108:111]
	v_mfma_f32_16x16x32_bf16 v[100:103], v[160:163], v[208:211], v[100:103]
	v_mfma_f32_16x16x32_bf16 v[88:91], v[152:155], v[216:219], v[88:91]
	v_mfma_f32_16x16x32_bf16 v[84:87], v[160:163], v[216:219], v[84:87]
	v_mfma_f32_16x16x32_bf16 v[56:59], v[152:155], v[224:227], v[56:59]
	v_mfma_f32_16x16x32_bf16 v[44:47], v[160:163], v[224:227], v[44:47]
	s_setprio 0
	s_barrier
	s_add_i32 s33, 0, 0x1c000
	s_add_i32 s7, s7, s87
	s_add_u32 s2, s2, s94
	v_add_u32_e32 v244, s33, v165
	v_lshl_add_u64 v[248:249], v[248:249], 0, s[16:17]
	s_mov_b32 m0, s7
	s_addc_u32 s3, s3, s95
	ds_read_b128 v[232:235], v244
	ds_read_b128 v[236:239], v244 offset:1024
	ds_read_b128 v[240:243], v244 offset:2048
	ds_read_b128 v[244:247], v244 offset:3072
	global_load_lds_dwordx4 v[248:249], off
	v_lshl_add_u64 v[248:249], s[2:3], 0, v[138:139]
	v_lshl_add_u64 v[248:249], v[248:249], 0, s[16:17]
	s_add_i32 m0, s7, 0x2000
	s_nop 0
	global_load_lds_dwordx4 v[248:249], off
	s_barrier
	s_waitcnt lgkmcnt(0)
	s_setprio 1
	s_waitcnt lgkmcnt(0)
	v_mfma_f32_16x16x32_bf16 v[120:123], v[232:235], v[196:199], v[120:123]
	v_mfma_f32_16x16x32_bf16 v[116:119], v[240:243], v[196:199], v[116:119]
	v_mfma_f32_16x16x32_bf16 v[112:115], v[232:235], v[204:207], v[112:115]
	v_mfma_f32_16x16x32_bf16 v[104:107], v[240:243], v[204:207], v[104:107]
	v_mfma_f32_16x16x32_bf16 v[96:99], v[232:235], v[212:215], v[96:99]
	v_mfma_f32_16x16x32_bf16 v[92:95], v[240:243], v[212:215], v[92:95]
	v_mfma_f32_16x16x32_bf16 v[80:83], v[232:235], v[220:223], v[80:83]
	v_mfma_f32_16x16x32_bf16 v[76:79], v[240:243], v[220:223], v[76:79]
	v_mfma_f32_16x16x32_bf16 v[120:123], v[236:239], v[200:203], v[120:123]
	v_mfma_f32_16x16x32_bf16 v[116:119], v[244:247], v[200:203], v[116:119]
	v_mfma_f32_16x16x32_bf16 v[112:115], v[236:239], v[208:211], v[112:115]
	v_mfma_f32_16x16x32_bf16 v[104:107], v[244:247], v[208:211], v[104:107]
	v_mfma_f32_16x16x32_bf16 v[96:99], v[236:239], v[216:219], v[96:99]
	v_mfma_f32_16x16x32_bf16 v[92:95], v[244:247], v[216:219], v[92:95]
	v_mfma_f32_16x16x32_bf16 v[80:83], v[236:239], v[224:227], v[80:83]
	v_mfma_f32_16x16x32_bf16 v[76:79], v[244:247], v[224:227], v[76:79]
	s_setprio 0
	s_add_u32 s8, s8, s96
	s_mov_b32 m0, s40
	v_lshl_add_u64 v[248:249], v[250:251], 0, s[16:17]
	s_addc_u32 s9, s9, s97
	s_barrier
	ds_read_b128 v[196:199], v195 offset:49152
	ds_read_b128 v[200:203], v195 offset:50176
	ds_read_b128 v[204:207], v195 offset:51200
	ds_read_b128 v[208:211], v195 offset:52224
	ds_read_b128 v[212:215], v195 offset:53248
	ds_read_b128 v[216:219], v195 offset:54272
	ds_read_b128 v[220:223], v195 offset:55296
	ds_read_b128 v[224:227], v195 offset:56320
	global_load_lds_dwordx4 v[248:249], off
	v_lshl_add_u64 v[248:249], s[8:9], 0, v[140:141]
	v_lshl_add_u64 v[248:249], v[248:249], 0, s[16:17]
	s_mov_b32 m0, s41
	s_nop 0
	global_load_lds_dwordx4 v[248:249], off
	s_barrier
	s_waitcnt lgkmcnt(0)
	s_setprio 1
	s_waitcnt lgkmcnt(0)
	v_mfma_f32_16x16x32_bf16 v[64:67], v[148:151], v[196:199], v[64:67]
	v_mfma_f32_16x16x32_bf16 v[60:63], v[156:159], v[196:199], v[60:63]
	v_mfma_f32_16x16x32_bf16 v[40:43], v[148:151], v[204:207], v[40:43]
	v_mfma_f32_16x16x32_bf16 v[36:39], v[156:159], v[204:207], v[36:39]
	v_mfma_f32_16x16x32_bf16 v[22:25], v[148:151], v[212:215], v[22:25]
	v_mfma_f32_16x16x32_bf16 v[18:21], v[156:159], v[212:215], v[18:21]
	v_mfma_f32_16x16x32_bf16 v[6:9], v[148:151], v[220:223], v[6:9]
	v_mfma_f32_16x16x32_bf16 v[2:5], v[156:159], v[220:223], v[2:5]
	v_mfma_f32_16x16x32_bf16 v[64:67], v[152:155], v[200:203], v[64:67]
	v_mfma_f32_16x16x32_bf16 v[60:63], v[160:163], v[200:203], v[60:63]
	v_mfma_f32_16x16x32_bf16 v[40:43], v[152:155], v[208:211], v[40:43]
	v_mfma_f32_16x16x32_bf16 v[36:39], v[160:163], v[208:211], v[36:39]
	v_mfma_f32_16x16x32_bf16 v[22:25], v[152:155], v[216:219], v[22:25]
	v_mfma_f32_16x16x32_bf16 v[18:21], v[160:163], v[216:219], v[18:21]
	v_mfma_f32_16x16x32_bf16 v[6:9], v[152:155], v[224:227], v[6:9]
	v_mfma_f32_16x16x32_bf16 v[2:5], v[160:163], v[224:227], v[2:5]
	s_setprio 0
	s_barrier
	s_add_u32 s2, s2, s34
	s_addc_u32 s3, s3, s35
	v_lshl_add_u64 v[148:149], s[2:3], 0, v[138:139]
	s_add_i32 s2, s33, s87
	v_lshl_add_u64 v[148:149], v[148:149], 0, s[16:17]
	s_mov_b32 m0, s2
	s_nop 0
	global_load_lds_dwordx4 v[148:149], off
	v_lshl_add_u64 v[148:149], v[252:253], 0, s[16:17]
	s_add_i32 m0, s2, 0x2000
	s_nop 0
	global_load_lds_dwordx4 v[148:149], off
	s_waitcnt vmcnt(6)
	s_barrier
	s_setprio 1
	v_mfma_f32_16x16x32_bf16 v[72:75], v[232:235], v[196:199], v[72:75]
	v_mfma_f32_16x16x32_bf16 v[68:71], v[240:243], v[196:199], v[68:71]
	v_mfma_f32_16x16x32_bf16 v[52:55], v[232:235], v[204:207], v[52:55]
	v_mfma_f32_16x16x32_bf16 v[48:51], v[240:243], v[204:207], v[48:51]
	v_mfma_f32_16x16x32_bf16 v[32:35], v[232:235], v[212:215], v[32:35]
	v_mfma_f32_16x16x32_bf16 v[28:31], v[240:243], v[212:215], v[28:31]
	v_mfma_f32_16x16x32_bf16 v[14:17], v[232:235], v[220:223], v[14:17]
	v_mfma_f32_16x16x32_bf16 v[10:13], v[240:243], v[220:223], v[10:13]
	v_mfma_f32_16x16x32_bf16 v[72:75], v[236:239], v[200:203], v[72:75]
	v_mfma_f32_16x16x32_bf16 v[68:71], v[244:247], v[200:203], v[68:71]
	v_mfma_f32_16x16x32_bf16 v[52:55], v[236:239], v[208:211], v[52:55]
	v_mfma_f32_16x16x32_bf16 v[48:51], v[244:247], v[208:211], v[48:51]
	v_mfma_f32_16x16x32_bf16 v[32:35], v[236:239], v[216:219], v[32:35]
	v_mfma_f32_16x16x32_bf16 v[28:31], v[244:247], v[216:219], v[28:31]
	v_mfma_f32_16x16x32_bf16 v[14:17], v[236:239], v[224:227], v[14:17]
	v_mfma_f32_16x16x32_bf16 v[10:13], v[244:247], v[224:227], v[10:13]
	s_setprio 0
	s_add_u32 s0, s0, 0x100
	s_addc_u32 s1, s1, 0
	v_lshl_add_u64 v[134:135], v[134:135], 0, s[20:21]
	v_lshl_add_u64 v[132:133], v[132:133], 0, s[20:21]
	s_cmp_ge_u32 s6, s86
	s_mov_b32 s2, s6
	s_barrier
	s_cbranch_scc0 .LBB0_894
	s_and_b64 vcc, exec, s[26:27]
	s_cbranch_vccz .LBB0_1126
	v_add_u32_e32 v148, s81, v166
	v_add_u32_e32 v132, s62, v168
	s_mov_b64 s[2:3], -1
	s_mov_b64 s[0:1], 0
	s_cmp_lt_i32 s63, 4
	s_mov_b64 s[76:77], 0
	s_cbranch_scc1 .LBB0_928
	s_cmp_gt_i32 s63, 6
	s_cbranch_scc0 .LBB0_921
	s_cmp_gt_i32 s63, 7
	s_cbranch_scc0 .LBB0_902
	s_cmp_eq_u32 s63, 8
	s_mov_b64 s[76:77], -1
	s_cbranch_scc0 .LBB0_901
	v_ashrrev_i32_e32 v149, 31, v148
	v_lshl_add_u64 v[134:135], v[148:149], 2, s[42:43]
	global_load_dword v198, v[134:135], off
	global_load_dword v200, v[134:135], off offset:64
	global_load_dword v202, v[134:135], off offset:128
	global_load_dword v204, v[134:135], off offset:192
	global_load_dword v206, v[134:135], off offset:512
	global_load_dword v208, v[134:135], off offset:576
	global_load_dword v210, v[134:135], off offset:640
	global_load_dword v212, v[134:135], off offset:704
	s_mov_b32 s6, 0x800000
	v_add_u32_e32 v152, v132, v167
	v_mov_b64_e32 v[150:151], s[44:45]
	s_movk_i32 s7, 0x2c00
	v_ashrrev_i32_e32 v153, 31, v152
	v_mad_i64_i32 v[160:161], s[2:3], v148, s7, v[150:151]
	v_lshlrev_b64 v[152:153], 1, v[152:153]
	v_lshl_add_u64 v[160:161], v[160:161], 0, v[152:153]
	s_mov_b64 s[2:3], 0x2c000
	v_lshl_add_u64 v[214:215], v[160:161], 0, s[2:3]
	v_lshl_add_u64 v[216:217], v[214:215], 0, s[2:3]
	v_lshl_add_u64 v[218:219], v[216:217], 0, s[2:3]
	s_mov_b64 s[2:3], 0x160000
	v_lshl_add_u64 v[220:221], v[160:161], 0, s[2:3]
	v_lshl_add_u64 v[222:223], v[214:215], 0, s[2:3]
	v_lshl_add_u64 v[224:225], v[216:217], 0, s[2:3]
	v_lshl_add_u64 v[226:227], v[218:219], 0, s[2:3]
	s_mov_b64 s[76:77], 0
	s_waitcnt vmcnt(0)
	v_fmamk_f32 v198, v198, 0x3a800000, v172
	v_fmamk_f32 v200, v200, 0x3a800000, v172
	v_fmamk_f32 v202, v202, 0x3a800000, v172
	v_fmamk_f32 v204, v204, 0x3a800000, v172
	v_fmamk_f32 v206, v206, 0x3a800000, v172
	v_fmamk_f32 v208, v208, 0x3a800000, v172
	v_fmamk_f32 v210, v210, 0x3a800000, v172
	v_fmamk_f32 v212, v212, 0x3a800000, v172
	v_rsq_f32_e32 v198, v198
	v_rsq_f32_e32 v200, v200
	v_rsq_f32_e32 v202, v202
	v_rsq_f32_e32 v204, v204
	v_rsq_f32_e32 v206, v206
	v_rsq_f32_e32 v208, v208
	v_rsq_f32_e32 v210, v210
	v_rsq_f32_e32 v212, v212
	s_nop 0
	v_pk_mul_f32 v[128:129], v[128:129], v[198:199] op_sel_hi:[1,0]
	v_pk_mul_f32 v[130:131], v[130:131], v[198:199] op_sel_hi:[1,0]
	v_pk_mul_f32 v[124:125], v[124:125], v[198:199] op_sel_hi:[1,0]
	v_pk_mul_f32 v[126:127], v[126:127], v[198:199] op_sel_hi:[1,0]
	v_cvt_pk_bf16_f32 v128, v128, v129
	v_cvt_pk_bf16_f32 v129, v130, v131
	v_cvt_pk_bf16_f32 v130, v124, v125
	v_cvt_pk_bf16_f32 v131, v126, v127
	global_store_dwordx4 v[160:161], v[128:131], off
	v_pk_mul_f32 v[120:121], v[120:121], v[198:199] op_sel_hi:[1,0]
	v_pk_mul_f32 v[122:123], v[122:123], v[198:199] op_sel_hi:[1,0]
	v_pk_mul_f32 v[116:117], v[116:117], v[198:199] op_sel_hi:[1,0]
	v_pk_mul_f32 v[118:119], v[118:119], v[198:199] op_sel_hi:[1,0]
	v_cvt_pk_bf16_f32 v120, v120, v121
	v_cvt_pk_bf16_f32 v121, v122, v123
	v_cvt_pk_bf16_f32 v122, v116, v117
	v_cvt_pk_bf16_f32 v123, v118, v119
	global_store_dwordx4 v[160:161], v[120:123], off offset:256
	v_pk_mul_f32 v[108:109], v[108:109], v[200:201] op_sel_hi:[1,0]
	v_pk_mul_f32 v[110:111], v[110:111], v[200:201] op_sel_hi:[1,0]
	v_pk_mul_f32 v[100:101], v[100:101], v[200:201] op_sel_hi:[1,0]
	v_pk_mul_f32 v[102:103], v[102:103], v[200:201] op_sel_hi:[1,0]
	v_cvt_pk_bf16_f32 v108, v108, v109
	v_cvt_pk_bf16_f32 v109, v110, v111
	v_cvt_pk_bf16_f32 v110, v100, v101
	v_cvt_pk_bf16_f32 v111, v102, v103
	global_store_dwordx4 v[214:215], v[108:111], off
	v_pk_mul_f32 v[112:113], v[112:113], v[200:201] op_sel_hi:[1,0]
	v_pk_mul_f32 v[114:115], v[114:115], v[200:201] op_sel_hi:[1,0]
	v_pk_mul_f32 v[104:105], v[104:105], v[200:201] op_sel_hi:[1,0]
	v_pk_mul_f32 v[106:107], v[106:107], v[200:201] op_sel_hi:[1,0]
	v_cvt_pk_bf16_f32 v112, v112, v113
	v_cvt_pk_bf16_f32 v113, v114, v115
	v_cvt_pk_bf16_f32 v114, v104, v105
	v_cvt_pk_bf16_f32 v115, v106, v107
	global_store_dwordx4 v[214:215], v[112:115], off offset:256
	v_pk_mul_f32 v[88:89], v[88:89], v[202:203] op_sel_hi:[1,0]
	v_pk_mul_f32 v[90:91], v[90:91], v[202:203] op_sel_hi:[1,0]
	v_pk_mul_f32 v[84:85], v[84:85], v[202:203] op_sel_hi:[1,0]
	v_pk_mul_f32 v[86:87], v[86:87], v[202:203] op_sel_hi:[1,0]
	v_cvt_pk_bf16_f32 v88, v88, v89
	v_cvt_pk_bf16_f32 v89, v90, v91
	v_cvt_pk_bf16_f32 v90, v84, v85
	v_cvt_pk_bf16_f32 v91, v86, v87
	global_store_dwordx4 v[216:217], v[88:91], off
	v_pk_mul_f32 v[96:97], v[96:97], v[202:203] op_sel_hi:[1,0]
	v_pk_mul_f32 v[98:99], v[98:99], v[202:203] op_sel_hi:[1,0]
	v_pk_mul_f32 v[92:93], v[92:93], v[202:203] op_sel_hi:[1,0]
	v_pk_mul_f32 v[94:95], v[94:95], v[202:203] op_sel_hi:[1,0]
	v_cvt_pk_bf16_f32 v96, v96, v97
	v_cvt_pk_bf16_f32 v97, v98, v99
	v_cvt_pk_bf16_f32 v98, v92, v93
	v_cvt_pk_bf16_f32 v99, v94, v95
	global_store_dwordx4 v[216:217], v[96:99], off offset:256
	v_pk_mul_f32 v[56:57], v[56:57], v[204:205] op_sel_hi:[1,0]
	v_pk_mul_f32 v[58:59], v[58:59], v[204:205] op_sel_hi:[1,0]
	v_pk_mul_f32 v[44:45], v[44:45], v[204:205] op_sel_hi:[1,0]
	v_pk_mul_f32 v[46:47], v[46:47], v[204:205] op_sel_hi:[1,0]
	v_cvt_pk_bf16_f32 v56, v56, v57
	v_cvt_pk_bf16_f32 v57, v58, v59
	v_cvt_pk_bf16_f32 v58, v44, v45
	v_cvt_pk_bf16_f32 v59, v46, v47
	global_store_dwordx4 v[218:219], v[56:59], off
	v_pk_mul_f32 v[80:81], v[80:81], v[204:205] op_sel_hi:[1,0]
	v_pk_mul_f32 v[82:83], v[82:83], v[204:205] op_sel_hi:[1,0]
	v_pk_mul_f32 v[76:77], v[76:77], v[204:205] op_sel_hi:[1,0]
	v_pk_mul_f32 v[78:79], v[78:79], v[204:205] op_sel_hi:[1,0]
	v_cvt_pk_bf16_f32 v80, v80, v81
	v_cvt_pk_bf16_f32 v81, v82, v83
	v_cvt_pk_bf16_f32 v82, v76, v77
	v_cvt_pk_bf16_f32 v83, v78, v79
	global_store_dwordx4 v[218:219], v[80:83], off offset:256
	v_pk_mul_f32 v[64:65], v[64:65], v[206:207] op_sel_hi:[1,0]
	v_pk_mul_f32 v[66:67], v[66:67], v[206:207] op_sel_hi:[1,0]
	v_pk_mul_f32 v[60:61], v[60:61], v[206:207] op_sel_hi:[1,0]
	v_pk_mul_f32 v[62:63], v[62:63], v[206:207] op_sel_hi:[1,0]
	v_cvt_pk_bf16_f32 v64, v64, v65
	v_cvt_pk_bf16_f32 v65, v66, v67
	v_cvt_pk_bf16_f32 v66, v60, v61
	v_cvt_pk_bf16_f32 v67, v62, v63
	global_store_dwordx4 v[220:221], v[64:67], off
	v_pk_mul_f32 v[72:73], v[72:73], v[206:207] op_sel_hi:[1,0]
	v_pk_mul_f32 v[74:75], v[74:75], v[206:207] op_sel_hi:[1,0]
	v_pk_mul_f32 v[68:69], v[68:69], v[206:207] op_sel_hi:[1,0]
	v_pk_mul_f32 v[70:71], v[70:71], v[206:207] op_sel_hi:[1,0]
	v_cvt_pk_bf16_f32 v72, v72, v73
	v_cvt_pk_bf16_f32 v73, v74, v75
	v_cvt_pk_bf16_f32 v74, v68, v69
	v_cvt_pk_bf16_f32 v75, v70, v71
	global_store_dwordx4 v[220:221], v[72:75], off offset:256
	v_pk_mul_f32 v[40:41], v[40:41], v[208:209] op_sel_hi:[1,0]
	v_pk_mul_f32 v[42:43], v[42:43], v[208:209] op_sel_hi:[1,0]
	v_pk_mul_f32 v[36:37], v[36:37], v[208:209] op_sel_hi:[1,0]
	v_pk_mul_f32 v[38:39], v[38:39], v[208:209] op_sel_hi:[1,0]
	v_cvt_pk_bf16_f32 v40, v40, v41
	v_cvt_pk_bf16_f32 v41, v42, v43
	v_cvt_pk_bf16_f32 v42, v36, v37
	v_cvt_pk_bf16_f32 v43, v38, v39
	global_store_dwordx4 v[222:223], v[40:43], off
	v_pk_mul_f32 v[52:53], v[52:53], v[208:209] op_sel_hi:[1,0]
	v_pk_mul_f32 v[54:55], v[54:55], v[208:209] op_sel_hi:[1,0]
	v_pk_mul_f32 v[48:49], v[48:49], v[208:209] op_sel_hi:[1,0]
	v_pk_mul_f32 v[50:51], v[50:51], v[208:209] op_sel_hi:[1,0]
	v_cvt_pk_bf16_f32 v52, v52, v53
	v_cvt_pk_bf16_f32 v53, v54, v55
	v_cvt_pk_bf16_f32 v54, v48, v49
	v_cvt_pk_bf16_f32 v55, v50, v51
	global_store_dwordx4 v[222:223], v[52:55], off offset:256
	v_pk_mul_f32 v[22:23], v[22:23], v[210:211] op_sel_hi:[1,0]
	v_pk_mul_f32 v[24:25], v[24:25], v[210:211] op_sel_hi:[1,0]
	v_pk_mul_f32 v[18:19], v[18:19], v[210:211] op_sel_hi:[1,0]
	v_pk_mul_f32 v[20:21], v[20:21], v[210:211] op_sel_hi:[1,0]
	v_cvt_pk_bf16_f32 v22, v22, v23
	v_cvt_pk_bf16_f32 v23, v24, v25
	v_cvt_pk_bf16_f32 v24, v18, v19
	v_cvt_pk_bf16_f32 v25, v20, v21
	global_store_dwordx4 v[224:225], v[22:25], off
	v_pk_mul_f32 v[32:33], v[32:33], v[210:211] op_sel_hi:[1,0]
	v_pk_mul_f32 v[34:35], v[34:35], v[210:211] op_sel_hi:[1,0]
	v_pk_mul_f32 v[28:29], v[28:29], v[210:211] op_sel_hi:[1,0]
	v_pk_mul_f32 v[30:31], v[30:31], v[210:211] op_sel_hi:[1,0]
	v_cvt_pk_bf16_f32 v32, v32, v33
	v_cvt_pk_bf16_f32 v33, v34, v35
	v_cvt_pk_bf16_f32 v34, v28, v29
	v_cvt_pk_bf16_f32 v35, v30, v31
	global_store_dwordx4 v[224:225], v[32:35], off offset:256
	v_pk_mul_f32 v[6:7], v[6:7], v[212:213] op_sel_hi:[1,0]
	v_pk_mul_f32 v[8:9], v[8:9], v[212:213] op_sel_hi:[1,0]
	v_pk_mul_f32 v[2:3], v[2:3], v[212:213] op_sel_hi:[1,0]
	v_pk_mul_f32 v[4:5], v[4:5], v[212:213] op_sel_hi:[1,0]
	v_cvt_pk_bf16_f32 v6, v6, v7
	v_cvt_pk_bf16_f32 v7, v8, v9
	v_cvt_pk_bf16_f32 v8, v2, v3
	v_cvt_pk_bf16_f32 v9, v4, v5
	global_store_dwordx4 v[226:227], v[6:9], off
	v_pk_mul_f32 v[14:15], v[14:15], v[212:213] op_sel_hi:[1,0]
	v_pk_mul_f32 v[16:17], v[16:17], v[212:213] op_sel_hi:[1,0]
	v_pk_mul_f32 v[10:11], v[10:11], v[212:213] op_sel_hi:[1,0]
	v_pk_mul_f32 v[12:13], v[12:13], v[212:213] op_sel_hi:[1,0]
	v_cvt_pk_bf16_f32 v14, v14, v15
	v_cvt_pk_bf16_f32 v15, v16, v17
	v_cvt_pk_bf16_f32 v16, v10, v11
	v_cvt_pk_bf16_f32 v17, v12, v13
	global_store_dwordx4 v[226:227], v[14:17], off offset:256

.LBB0_924:
	s_andn2_b64 vcc, exec, s[2:3]
	s_cbranch_vccnz .LBB0_927
	s_cmp_eq_u32 s63, 4
	s_mov_b64 s[76:77], -1
	s_cbranch_scc0 .LBB0_927
	v_ashrrev_i32_e32 v149, 31, v148
	s_waitcnt lgkmcnt(0)
	v_lshl_add_u64 v[134:135], v[148:149], 2, s[50:51]
	global_load_dword v198, v[134:135], off
	global_load_dword v200, v[134:135], off offset:64
	global_load_dword v202, v[134:135], off offset:128
	global_load_dword v204, v[134:135], off offset:192
	global_load_dword v206, v[134:135], off offset:512
	global_load_dword v208, v[134:135], off offset:576
	global_load_dword v210, v[134:135], off offset:640
	global_load_dword v212, v[134:135], off offset:704
	v_add_u32_e32 v150, v132, v167
	v_lshlrev_b64 v[152:153], 11, v[148:149]
	v_lshl_add_u64 v[158:159], s[52:53], 0, v[152:153]
	v_ashrrev_i32_e32 v151, 31, v150
	v_lshl_add_u64 v[160:161], v[150:151], 1, v[158:159]
	s_mov_b64 s[2:3], 0x8000
	v_lshl_add_u64 v[214:215], v[160:161], 0, s[2:3]
	v_lshl_add_u64 v[216:217], v[214:215], 0, s[2:3]
	v_lshl_add_u64 v[218:219], v[216:217], 0, s[2:3]
	s_mov_b64 s[2:3], 0x40000
	v_lshl_add_u64 v[220:221], v[160:161], 0, s[2:3]
	v_lshl_add_u64 v[222:223], v[214:215], 0, s[2:3]
	v_lshl_add_u64 v[224:225], v[216:217], 0, s[2:3]
	v_lshl_add_u64 v[226:227], v[218:219], 0, s[2:3]
	s_mov_b64 s[76:77], 0
	s_waitcnt vmcnt(0)
	v_fmamk_f32 v198, v198, 0x3a800000, v172
	v_fmamk_f32 v200, v200, 0x3a800000, v172
	v_fmamk_f32 v202, v202, 0x3a800000, v172
	v_fmamk_f32 v204, v204, 0x3a800000, v172
	v_fmamk_f32 v206, v206, 0x3a800000, v172
	v_fmamk_f32 v208, v208, 0x3a800000, v172
	v_fmamk_f32 v210, v210, 0x3a800000, v172
	v_fmamk_f32 v212, v212, 0x3a800000, v172
	v_rsq_f32_e32 v198, v198
	v_rsq_f32_e32 v200, v200
	v_rsq_f32_e32 v202, v202
	v_rsq_f32_e32 v204, v204
	v_rsq_f32_e32 v206, v206
	v_rsq_f32_e32 v208, v208
	v_rsq_f32_e32 v210, v210
	v_rsq_f32_e32 v212, v212
	s_nop 0
	v_mul_f32_e32 v198, 0x3d800000, v198
	v_mul_f32_e32 v200, 0x3d800000, v200
	v_mul_f32_e32 v202, 0x3d800000, v202
	v_mul_f32_e32 v204, 0x3d800000, v204
	v_mul_f32_e32 v206, 0x3d800000, v206
	v_mul_f32_e32 v208, 0x3d800000, v208
	v_mul_f32_e32 v210, 0x3d800000, v210
	v_mul_f32_e32 v212, 0x3d800000, v212
	v_pk_mul_f32 v[128:129], v[128:129], v[198:199] op_sel_hi:[1,0]
	v_pk_mul_f32 v[130:131], v[130:131], v[198:199] op_sel_hi:[1,0]
	v_pk_mul_f32 v[124:125], v[124:125], v[198:199] op_sel_hi:[1,0]
	v_pk_mul_f32 v[126:127], v[126:127], v[198:199] op_sel_hi:[1,0]
	v_cvt_pk_bf16_f32 v128, v128, v129
	v_cvt_pk_bf16_f32 v129, v130, v131
	v_cvt_pk_bf16_f32 v130, v124, v125
	v_cvt_pk_bf16_f32 v131, v126, v127
	global_store_dwordx4 v[160:161], v[128:131], off
	v_pk_mul_f32 v[120:121], v[120:121], v[198:199] op_sel_hi:[1,0]
	v_pk_mul_f32 v[122:123], v[122:123], v[198:199] op_sel_hi:[1,0]
	v_pk_mul_f32 v[116:117], v[116:117], v[198:199] op_sel_hi:[1,0]
	v_pk_mul_f32 v[118:119], v[118:119], v[198:199] op_sel_hi:[1,0]
	v_cvt_pk_bf16_f32 v120, v120, v121
	v_cvt_pk_bf16_f32 v121, v122, v123
	v_cvt_pk_bf16_f32 v122, v116, v117
	v_cvt_pk_bf16_f32 v123, v118, v119
	global_store_dwordx4 v[160:161], v[120:123], off offset:256
	v_pk_mul_f32 v[108:109], v[108:109], v[200:201] op_sel_hi:[1,0]
	v_pk_mul_f32 v[110:111], v[110:111], v[200:201] op_sel_hi:[1,0]
	v_pk_mul_f32 v[100:101], v[100:101], v[200:201] op_sel_hi:[1,0]
	v_pk_mul_f32 v[102:103], v[102:103], v[200:201] op_sel_hi:[1,0]
	v_cvt_pk_bf16_f32 v108, v108, v109
	v_cvt_pk_bf16_f32 v109, v110, v111
	v_cvt_pk_bf16_f32 v110, v100, v101
	v_cvt_pk_bf16_f32 v111, v102, v103
	global_store_dwordx4 v[214:215], v[108:111], off
	v_pk_mul_f32 v[112:113], v[112:113], v[200:201] op_sel_hi:[1,0]
	v_pk_mul_f32 v[114:115], v[114:115], v[200:201] op_sel_hi:[1,0]
	v_pk_mul_f32 v[104:105], v[104:105], v[200:201] op_sel_hi:[1,0]
	v_pk_mul_f32 v[106:107], v[106:107], v[200:201] op_sel_hi:[1,0]
	v_cvt_pk_bf16_f32 v112, v112, v113
	v_cvt_pk_bf16_f32 v113, v114, v115
	v_cvt_pk_bf16_f32 v114, v104, v105
	v_cvt_pk_bf16_f32 v115, v106, v107
	global_store_dwordx4 v[214:215], v[112:115], off offset:256
	v_pk_mul_f32 v[88:89], v[88:89], v[202:203] op_sel_hi:[1,0]
	v_pk_mul_f32 v[90:91], v[90:91], v[202:203] op_sel_hi:[1,0]
	v_pk_mul_f32 v[84:85], v[84:85], v[202:203] op_sel_hi:[1,0]
	v_pk_mul_f32 v[86:87], v[86:87], v[202:203] op_sel_hi:[1,0]
	v_cvt_pk_bf16_f32 v88, v88, v89
	v_cvt_pk_bf16_f32 v89, v90, v91
	v_cvt_pk_bf16_f32 v90, v84, v85
	v_cvt_pk_bf16_f32 v91, v86, v87
	global_store_dwordx4 v[216:217], v[88:91], off
	v_pk_mul_f32 v[96:97], v[96:97], v[202:203] op_sel_hi:[1,0]
	v_pk_mul_f32 v[98:99], v[98:99], v[202:203] op_sel_hi:[1,0]
	v_pk_mul_f32 v[92:93], v[92:93], v[202:203] op_sel_hi:[1,0]
	v_pk_mul_f32 v[94:95], v[94:95], v[202:203] op_sel_hi:[1,0]
	v_cvt_pk_bf16_f32 v96, v96, v97
	v_cvt_pk_bf16_f32 v97, v98, v99
	v_cvt_pk_bf16_f32 v98, v92, v93
	v_cvt_pk_bf16_f32 v99, v94, v95
	global_store_dwordx4 v[216:217], v[96:99], off offset:256
	v_pk_mul_f32 v[56:57], v[56:57], v[204:205] op_sel_hi:[1,0]
	v_pk_mul_f32 v[58:59], v[58:59], v[204:205] op_sel_hi:[1,0]
	v_pk_mul_f32 v[44:45], v[44:45], v[204:205] op_sel_hi:[1,0]
	v_pk_mul_f32 v[46:47], v[46:47], v[204:205] op_sel_hi:[1,0]
	v_cvt_pk_bf16_f32 v56, v56, v57
	v_cvt_pk_bf16_f32 v57, v58, v59
	v_cvt_pk_bf16_f32 v58, v44, v45
	v_cvt_pk_bf16_f32 v59, v46, v47
	global_store_dwordx4 v[218:219], v[56:59], off
	v_pk_mul_f32 v[80:81], v[80:81], v[204:205] op_sel_hi:[1,0]
	v_pk_mul_f32 v[82:83], v[82:83], v[204:205] op_sel_hi:[1,0]
	v_pk_mul_f32 v[76:77], v[76:77], v[204:205] op_sel_hi:[1,0]
	v_pk_mul_f32 v[78:79], v[78:79], v[204:205] op_sel_hi:[1,0]
	v_cvt_pk_bf16_f32 v80, v80, v81
	v_cvt_pk_bf16_f32 v81, v82, v83
	v_cvt_pk_bf16_f32 v82, v76, v77
	v_cvt_pk_bf16_f32 v83, v78, v79
	global_store_dwordx4 v[218:219], v[80:83], off offset:256
	v_pk_mul_f32 v[64:65], v[64:65], v[206:207] op_sel_hi:[1,0]
	v_pk_mul_f32 v[66:67], v[66:67], v[206:207] op_sel_hi:[1,0]
	v_pk_mul_f32 v[60:61], v[60:61], v[206:207] op_sel_hi:[1,0]
	v_pk_mul_f32 v[62:63], v[62:63], v[206:207] op_sel_hi:[1,0]
	v_cvt_pk_bf16_f32 v64, v64, v65
	v_cvt_pk_bf16_f32 v65, v66, v67
	v_cvt_pk_bf16_f32 v66, v60, v61
	v_cvt_pk_bf16_f32 v67, v62, v63
	global_store_dwordx4 v[220:221], v[64:67], off
	v_pk_mul_f32 v[72:73], v[72:73], v[206:207] op_sel_hi:[1,0]
	v_pk_mul_f32 v[74:75], v[74:75], v[206:207] op_sel_hi:[1,0]
	v_pk_mul_f32 v[68:69], v[68:69], v[206:207] op_sel_hi:[1,0]
	v_pk_mul_f32 v[70:71], v[70:71], v[206:207] op_sel_hi:[1,0]
	v_cvt_pk_bf16_f32 v72, v72, v73
	v_cvt_pk_bf16_f32 v73, v74, v75
	v_cvt_pk_bf16_f32 v74, v68, v69
	v_cvt_pk_bf16_f32 v75, v70, v71
	global_store_dwordx4 v[220:221], v[72:75], off offset:256
	v_pk_mul_f32 v[40:41], v[40:41], v[208:209] op_sel_hi:[1,0]
	v_pk_mul_f32 v[42:43], v[42:43], v[208:209] op_sel_hi:[1,0]
	v_pk_mul_f32 v[36:37], v[36:37], v[208:209] op_sel_hi:[1,0]
	v_pk_mul_f32 v[38:39], v[38:39], v[208:209] op_sel_hi:[1,0]
	v_cvt_pk_bf16_f32 v40, v40, v41
	v_cvt_pk_bf16_f32 v41, v42, v43
	v_cvt_pk_bf16_f32 v42, v36, v37
	v_cvt_pk_bf16_f32 v43, v38, v39
	global_store_dwordx4 v[222:223], v[40:43], off
	v_pk_mul_f32 v[52:53], v[52:53], v[208:209] op_sel_hi:[1,0]
	v_pk_mul_f32 v[54:55], v[54:55], v[208:209] op_sel_hi:[1,0]
	v_pk_mul_f32 v[48:49], v[48:49], v[208:209] op_sel_hi:[1,0]
	v_pk_mul_f32 v[50:51], v[50:51], v[208:209] op_sel_hi:[1,0]
	v_cvt_pk_bf16_f32 v52, v52, v53
	v_cvt_pk_bf16_f32 v53, v54, v55
	v_cvt_pk_bf16_f32 v54, v48, v49
	v_cvt_pk_bf16_f32 v55, v50, v51
	global_store_dwordx4 v[222:223], v[52:55], off offset:256
	v_pk_mul_f32 v[22:23], v[22:23], v[210:211] op_sel_hi:[1,0]
	v_pk_mul_f32 v[24:25], v[24:25], v[210:211] op_sel_hi:[1,0]
	v_pk_mul_f32 v[18:19], v[18:19], v[210:211] op_sel_hi:[1,0]
	v_pk_mul_f32 v[20:21], v[20:21], v[210:211] op_sel_hi:[1,0]
	v_cvt_pk_bf16_f32 v22, v22, v23
	v_cvt_pk_bf16_f32 v23, v24, v25
	v_cvt_pk_bf16_f32 v24, v18, v19
	v_cvt_pk_bf16_f32 v25, v20, v21
	global_store_dwordx4 v[224:225], v[22:25], off
	v_pk_mul_f32 v[32:33], v[32:33], v[210:211] op_sel_hi:[1,0]
	v_pk_mul_f32 v[34:35], v[34:35], v[210:211] op_sel_hi:[1,0]
	v_pk_mul_f32 v[28:29], v[28:29], v[210:211] op_sel_hi:[1,0]
	v_pk_mul_f32 v[30:31], v[30:31], v[210:211] op_sel_hi:[1,0]
	v_cvt_pk_bf16_f32 v32, v32, v33
	v_cvt_pk_bf16_f32 v33, v34, v35
	v_cvt_pk_bf16_f32 v34, v28, v29
	v_cvt_pk_bf16_f32 v35, v30, v31
	global_store_dwordx4 v[224:225], v[32:35], off offset:256
	v_pk_mul_f32 v[6:7], v[6:7], v[212:213] op_sel_hi:[1,0]
	v_pk_mul_f32 v[8:9], v[8:9], v[212:213] op_sel_hi:[1,0]
	v_pk_mul_f32 v[2:3], v[2:3], v[212:213] op_sel_hi:[1,0]
	v_pk_mul_f32 v[4:5], v[4:5], v[212:213] op_sel_hi:[1,0]
	v_cvt_pk_bf16_f32 v6, v6, v7
	v_cvt_pk_bf16_f32 v7, v8, v9
	v_cvt_pk_bf16_f32 v8, v2, v3
	v_cvt_pk_bf16_f32 v9, v4, v5
	global_store_dwordx4 v[226:227], v[6:9], off
	v_pk_mul_f32 v[14:15], v[14:15], v[212:213] op_sel_hi:[1,0]
	v_pk_mul_f32 v[16:17], v[16:17], v[212:213] op_sel_hi:[1,0]
	v_pk_mul_f32 v[10:11], v[10:11], v[212:213] op_sel_hi:[1,0]
	v_pk_mul_f32 v[12:13], v[12:13], v[212:213] op_sel_hi:[1,0]
	v_cvt_pk_bf16_f32 v14, v14, v15
	v_cvt_pk_bf16_f32 v15, v16, v17
	v_cvt_pk_bf16_f32 v16, v10, v11
	v_cvt_pk_bf16_f32 v17, v12, v13
	global_store_dwordx4 v[226:227], v[14:17], off offset:256
